# loop-edge edit: neighbourhood-attention tile loop, slot/active SALU hoisted above the barrier and LDS reads issued before the next tile's LDS-DMA
# speedup vs baseline: 1.0051x; 1.0041x over previous
; #define LAS __attribute__((address_space(3)))
; #define DMA_TILE(t) do { const unsigned sl_ = (unsigned)__builtin_amdgcn_readfirstlane(ring0 + (unsigned)(((t) + base) % 3) * SLOT); \
;         glds16kv(loffk, loffv, kg + (size_t)(t) * 64 * PITCH, vg + (size_t)(t) * 64 * PITCH, sl_); } while (0)
; template <int MODE> ...
;     ...
;     auto head = [&](const int t) __attribute__((always_inline)) {
;         if (t >= 2) { if (t + 1 < nT || nK) asm volatile("s_waitcnt vmcnt(2)" ::: "memory"); else asm volatile("s_waitcnt vmcnt(0)" ::: "memory"); }
;         __builtin_amdgcn_s_barrier();
;         if (t + 2 < nT) DMA_TILE(t + 2); else if (nK) DMA_NEXT(t + 2 - nT);
;     };
;     auto body = [&](const int t) __attribute__((always_inline)) {
;         if (t >= act0 && t < act0 + actn) {
;         const LAS unsigned char* Sl = ring + ((t + base) % 3) * SLOT;
; #pragma unroll
;         for (int hf = 0; hf < NH; ++hf) {
;             if (MODE == 1) { const int ks = ktok0 + 64 * t + 32 * hf;
;                 if (ks + 31 < qtok0 - 128 || ks > qtok0 + 31 + 128) continue; }
;             bf16x8 kf[2][2][2];
; #pragma unroll
;             for (int jj = 0; jj < 2; ++jj)
; #pragma unroll
;                 for (int kt = 0; kt < 2; ++kt)
; #pragma unroll
;                     for (int ks = 0; ks < 2; ++ks) kf[jj][kt][ks] = *(const LAS bf16x8*)(Sl + kad[jj][ks] + (32 * hf + 16 * kt) * 128);
;             f32x4 bb[2][2];
; #pragma unroll
;             for (int jj = 0; jj < 2; ++jj) { const LAS f32x4* bl = bcp + ((MODE == 0) ? (dr0 + t - act0) * 8 : 16 * t + 8 * hf) + bofs[jj];
; #pragma unroll
;                 for (int kt = 0; kt < 2; ++kt) bb[jj][kt] = bl[4 * kt]; }
;             s16x4 vlo[2][4], vhi[2][4];
; #pragma unroll
;             for (int jj = 0; jj < 2; ++jj)
; #pragma unroll
;                 for (int dt = 0; dt < 4; ++dt) { const LAS unsigned char* vp = Sl + vad[jj] + (32 * hf) * 128 + ((dt ^ sv) << 5);
;                     vlo[jj][dt] = __builtin_bit_cast(s16x4, __builtin_amdgcn_ds_read_tr16_b64_v4i16((LAS s16x4*)(vp)));
;                     vhi[jj][dt] = __builtin_bit_cast(s16x4, __builtin_amdgcn_ds_read_tr16_b64_v4i16((LAS s16x4*)(vp + 2048))); }
.LBB0_301:
	s_add_i32 s0, s86, s65
	s_add_i32 s0, s0, 2
	s_mul_hi_i32 s14, s0, 0x55555556
	s_lshr_b32 s15, s14, 31
	s_add_i32 s14, s14, s15
	s_mul_i32 s14, s14, 3
	s_sub_i32 s0, s0, s14
	s_lshl_b32 s100, s0, 14
	s_add_i32 s0, s65, 2
	s_cmp_ge_i32 s0, s23
	s_cselect_b64 s[60:61], -1, 0
	s_cmp_lt_i32 s0, s45
	s_cselect_b64 s[66:67], -1, 0
	s_and_b64 s[60:61], s[60:61], s[66:67]
	s_cselect_b32 s101, 1, 0
	s_waitcnt vmcnt(2)
	s_barrier
	s_cmp_eq_u32 s101, 0
	s_cbranch_scc1 .Lna_dma_only
	v_add_u32_e32 v2, s100, v89
	v_add_u32_e32 v3, s100, v88
	ds_read_b128 v[130:133], v2
	ds_read_b128 v[134:137], v2 offset:2048
	ds_read_b128 v[138:141], v3
	ds_read_b128 v[142:145], v3 offset:2048
	v_add_u32_e32 v2, s100, v92
	v_add_u32_e32 v3, s100, v91
	ds_read_b128 v[146:149], v2
	ds_read_b128 v[150:153], v2 offset:2048
	ds_read_b128 v[154:157], v3
	ds_read_b128 v[158:161], v3 offset:2048
	v_add_u32_e32 v2, s50, v128
	v_add_u32_e32 v3, 0x10480, v2
	v_add_u32_e32 v2, 0x104c0, v2
	ds_read_b128 v[162:165], v3
	ds_read_b128 v[166:169], v2
	v_add_u32_e32 v2, s50, v127
	v_add_u32_e32 v3, 0x10480, v2
	v_add_u32_e32 v2, 0x104c0, v2
	ds_read_b128 v[170:173], v3
	ds_read_b128 v[174:177], v2
	v_add_u32_e32 v2, s100, v0
	v_add_u32_e32 v3, v2, v94
	v_add_u32_e32 v4, v2, v95
	ds_read_b64_tr_b16 v[78:79], v3 offset:8192
	ds_read_b64_tr_b16 v[80:81], v3 offset:10240
	ds_read_b64_tr_b16 v[74:75], v4 offset:8192
	ds_read_b64_tr_b16 v[76:77], v4 offset:10240
	v_add_u32_e32 v3, v2, v96
	v_add_u32_e32 v2, v2, v97
	ds_read_b64_tr_b16 v[70:71], v3 offset:8192
	ds_read_b64_tr_b16 v[72:73], v3 offset:10240
	ds_read_b64_tr_b16 v[66:67], v2 offset:8192
	ds_read_b64_tr_b16 v[68:69], v2 offset:10240
	v_add_u32_e32 v2, s100, v126
	v_add_u32_e32 v3, v2, v94
	v_add_u32_e32 v4, v2, v95
	ds_read_b64_tr_b16 v[14:15], v3 offset:8192
	ds_read_b64_tr_b16 v[16:17], v3 offset:10240
	ds_read_b64_tr_b16 v[10:11], v4 offset:8192
	ds_read_b64_tr_b16 v[12:13], v4 offset:10240
	v_add_u32_e32 v3, v2, v96
	v_add_u32_e32 v4, v2, v97
	ds_read_b64_tr_b16 v[6:7], v3 offset:8192
	ds_read_b64_tr_b16 v[8:9], v3 offset:10240
	ds_read_b64_tr_b16 v[2:3], v4 offset:8192
	ds_read_b64_tr_b16 v[4:5], v4 offset:10240
	s_add_i32 s0, s65, 4
	s_cmp_ge_i32 s0, s26
	s_cbranch_scc0 .Lna_tile_a
	s_mul_hi_u32 s0, s64, 0xaaaaaaab
	s_lshr_b32 s0, s0, 1
	s_mul_i32 s0, s0, 0xc000
	s_add_i32 s14, s51, s65
	s_sub_i32 s0, s53, s0
	s_mul_hi_u32 s15, s14, 0x48000
	s_mul_i32 s14, s14, 0x48000
	s_add_u32 s60, s34, s14
	s_addc_u32 s61, s35, s15
	s_add_u32 s66, s30, s14
	s_addc_u32 s67, s31, s15
	s_mov_b32 m0, s0
	s_nop 0
	global_load_lds_dwordx4 v84, s[60:61]
	s_add_u32 m0, m0, 0x2000
	s_nop 0
	global_load_lds_dwordx4 v85, s[66:67]
	s_branch .Lna_dmadone_a
.Lna_tile_a:
	s_add_i32 s0, s86, s65
	s_add_i32 s0, s0, 4
	s_mul_hi_i32 s14, s0, 0x55555556
	s_lshr_b32 s15, s14, 31
	s_add_i32 s14, s14, s15
	s_mul_i32 s14, s14, 3
	s_sub_i32 s0, s0, s14
	s_lshl_b32 s0, s0, 14
	s_add_i32 s0, s0, s94
	s_mov_b32 m0, s0
	s_nop 0
	global_load_lds_dwordx4 v84, s[42:43]
	s_add_u32 m0, m0, 0x2000
	s_nop 0
	global_load_lds_dwordx4 v85, s[46:47]
; template <int MODE> ...
;     ...
;     auto head = [&](const int t) __attribute__((always_inline)) {
;         if (t >= 2) { if (t + 1 < nT || nK) asm volatile("s_waitcnt vmcnt(2)" ::: "memory"); else asm volatile("s_waitcnt vmcnt(0)" ::: "memory"); }
;         __builtin_amdgcn_s_barrier();
;         if (t + 2 < nT) DMA_TILE(t + 2); else if (nK) DMA_NEXT(t + 2 - nT);
;     ...
;             f32x4 s[2][2];
; #pragma unroll
;             for (int jj = 0; jj < 2; ++jj)
; #pragma unroll
;                 for (int kt = 0; kt < 2; ++kt) { f32x4 a = (MODE == 0) ? bb[jj][kt] + mneg[jj][kt] : bb[jj][kt];
;                     a = __builtin_amdgcn_mfma_f32_16x16x32_bf16(kf[jj][kt][0], qf[jj][0], a, 0, 0, 0);
;                     s[jj][kt] = __builtin_amdgcn_mfma_f32_16x16x32_bf16(kf[jj][kt][1], qf[jj][1], a, 0, 0, 0); }
;             u32x4 pw[2];
; #pragma unroll
;             for (int jj = 0; jj < 2; ++jj) {
;                 const float tm = vmax3(vmax3(s[jj][0][0], s[jj][0][1], s[jj][0][2]), vmax3(s[jj][0][3], s[jj][1][0], s[jj][1][1]), vmax3(s[jj][1][2], s[jj][1][3], s[jj][1][3]));
;                 const float mn = quad_max3(mrun[jj], tm);
;                 const float alpha = __builtin_amdgcn_exp2f(mrun[jj] - mn);
;                 mrun[jj] = mn;
;                 float rsum = 0.f;
; #pragma unroll
;                 for (int kt = 0; kt < 2; ++kt)
; #pragma unroll
;                     for (int e = 0; e < 4; ++e) { s[jj][kt][e] = __builtin_amdgcn_exp2f(s[jj][kt][e] - mn); rsum += s[jj][kt][e]; }
;                 lrun[jj] = lrun[jj] * alpha + rsum;
; #pragma unroll
;                 for (int dt = 0; dt < 4; ++dt) o[jj][dt] *= alpha;
;                 pw[jj].x = cvtpk(s[jj][0][0], s[jj][0][1]); pw[jj].y = cvtpk(s[jj][0][2], s[jj][0][3]); pw[jj].z = cvtpk(s[jj][1][0], s[jj][1][1]); pw[jj].w = cvtpk(s[jj][1][2], s[jj][1][3]);
;             }
; #pragma unroll
;             for (int jj = 0; jj < 2; ++jj)
; #pragma unroll
;                 for (int dt = 0; dt < 4; ++dt) {
;                     const bf16x8 vf = (bf16x8){vlo[jj][dt][0], vlo[jj][dt][1], vlo[jj][dt][2], vlo[jj][dt][3], vhi[jj][dt][0], vhi[jj][dt][1], vhi[jj][dt][2], vhi[jj][dt][3]};
;                     o[jj][dt] = __builtin_amdgcn_mfma_f32_16x16x32_bf16(vf, __builtin_bit_cast(bf16x8, pw[jj]), o[jj][dt], 0, 0, 0); }
.Lna_dmadone_a:
	s_waitcnt lgkmcnt(14)
	v_pk_add_f32 v[164:165], v[112:113], v[164:165]
	v_pk_add_f32 v[162:163], v[110:111], v[162:163]
	s_nop 1
	v_mfma_f32_16x16x32_bf16 v[130:133], v[130:133], v[30:33], v[162:165]
	s_nop 2
	v_add_f32_e64 v164, v114, v168
	v_add_f32_e64 v165, v115, v169
	v_pk_add_f32 v[162:163], v[108:109], v[166:167]
	v_mfma_f32_16x16x32_bf16 v[130:133], v[138:141], v[26:29], v[130:133]
	v_add_f32_e64 v140, v106, v172
	v_add_f32_e64 v141, v107, v173
	v_pk_add_f32 v[138:139], v[102:103], v[170:171]
	v_mfma_f32_16x16x32_bf16 v[134:137], v[134:137], v[30:33], v[162:165]
	v_mfma_f32_16x16x32_bf16 v[134:137], v[142:145], v[26:29], v[134:137]
	s_nop 2
	v_maximum3_f32 v129, v130, v131, v132
	v_pk_add_f32 v[164:165], v[104:105], v[176:177]
	v_pk_add_f32 v[162:163], v[100:101], v[174:175]
	v_mfma_f32_16x16x32_bf16 v[138:141], v[146:149], v[22:25], v[138:141]
	v_mfma_f32_16x16x32_bf16 v[138:141], v[154:157], v[18:21], v[138:141]
	v_maximum3_f32 v142, v133, v134, v135
	v_maximum3_f32 v143, v136, v137, v137
	v_maximum3_f32 v129, v129, v142, v143
	v_mov_b32_e32 v142, v129
	s_nop 1
	v_permlane16_swap_b32_e32 v129, v142
	v_maximum3_f32 v129, v129, v142, v142
	v_mov_b32_e32 v142, v129
	s_nop 1
	v_permlane32_swap_b32_e32 v129, v142
	v_maximum3_f32 v129, v125, v129, v142
	v_mfma_f32_16x16x32_bf16 v[142:145], v[150:153], v[22:25], v[162:165]
	v_sub_f32_e32 v130, v130, v129
	v_exp_f32_e32 v146, v130
	v_sub_f32_e32 v130, v131, v129
	v_exp_f32_e32 v148, v130
	v_sub_f32_e32 v130, v132, v129
	v_mfma_f32_16x16x32_bf16 v[142:145], v[158:161], v[18:21], v[142:145]
	v_exp_f32_e32 v150, v130
	v_sub_f32_e32 v130, v133, v129
	v_exp_f32_e32 v152, v130
	v_sub_f32_e32 v130, v134, v129
	v_sub_f32_e32 v125, v125, v129
	v_exp_f32_e32 v134, v130
	v_sub_f32_e32 v130, v135, v129
	v_exp_f32_e32 v154, v130
	v_sub_f32_e32 v130, v136, v129
	v_exp_f32_e32 v136, v125
	v_sub_f32_e32 v125, v137, v129
	v_exp_f32_e32 v158, v125
	v_maximum3_f32 v125, v138, v139, v140
	v_maximum3_f32 v133, v141, v142, v143
	v_maximum3_f32 v135, v144, v145, v145
	v_maximum3_f32 v125, v125, v133, v135
	v_mov_b32_e32 v133, v125
	s_nop 1
	v_permlane16_swap_b32_e32 v125, v133
	v_maximum3_f32 v125, v125, v133, v133
	v_mov_b32_e32 v133, v125
	s_nop 1
	v_permlane32_swap_b32_e32 v125, v133
	v_maximum3_f32 v160, v124, v125, v133
	v_sub_f32_e32 v125, v138, v160
	v_sub_f32_e32 v135, v140, v160
	v_sub_f32_e32 v138, v143, v160
	v_exp_f32_e32 v156, v130
	v_pk_mul_f32 v[56:57], v[56:57], v[136:137] op_sel_hi:[1,0]
	v_pk_mul_f32 v[54:55], v[54:55], v[136:137] op_sel_hi:[1,0]
	v_pk_mul_f32 v[64:65], v[64:65], v[136:137] op_sel_hi:[1,0]
	v_pk_mul_f32 v[62:63], v[62:63], v[136:137] op_sel_hi:[1,0]
	v_pk_mul_f32 v[60:61], v[60:61], v[136:137] op_sel_hi:[1,0]
	v_pk_mul_f32 v[58:59], v[58:59], v[136:137] op_sel_hi:[1,0]
	v_pk_mul_f32 v[52:53], v[52:53], v[136:137] op_sel_hi:[1,0]
	v_pk_mul_f32 v[50:51], v[50:51], v[136:137] op_sel_hi:[1,0]
	v_sub_f32_e32 v137, v124, v160
	v_exp_f32_e32 v151, v135
	v_sub_f32_e32 v135, v141, v160
	v_exp_f32_e32 v155, v138
	v_sub_f32_e32 v138, v144, v160
	v_exp_f32_e32 v147, v125
	v_sub_f32_e32 v125, v139, v160
	v_exp_f32_e32 v153, v135
	v_sub_f32_e32 v135, v142, v160
	v_exp_f32_e32 v157, v138
	v_sub_f32_e32 v138, v145, v160
	v_exp_f32_e32 v137, v137
	v_exp_f32_e32 v149, v125
	v_exp_f32_e32 v135, v135
	v_exp_f32_e32 v159, v138
	v_cvt_pk_bf16_f32 v130, v146, v148
	v_cvt_pk_bf16_f32 v131, v150, v152
	v_cvt_pk_bf16_f32 v132, v134, v154
	v_cvt_pk_bf16_f32 v133, v156, v158
	v_pk_add_f32 v[124:125], v[146:147], 0 op_sel_hi:[1,0]
	s_waitcnt lgkmcnt(12)
	v_mfma_f32_16x16x32_bf16 v[62:65], v[74:77], v[130:133], v[62:65]
	v_mov_b32_e32 v76, v137
	v_pk_add_f32 v[124:125], v[148:149], v[124:125]
	v_pk_mul_f32 v[48:49], v[48:49], v[76:77] op_sel_hi:[1,0]
	s_waitcnt lgkmcnt(10)
	v_mfma_f32_16x16x32_bf16 v[58:61], v[70:73], v[130:133], v[58:61]
	v_mul_f32_e64 v46, v46, v76
	v_mul_f32_e64 v47, v47, v76
	v_cvt_pk_bf16_f32 v70, v147, v149
	v_cvt_pk_bf16_f32 v71, v151, v153
	v_cvt_pk_bf16_f32 v72, v135, v155
	v_cvt_pk_bf16_f32 v73, v157, v159
	v_mfma_f32_16x16x32_bf16 v[54:57], v[78:81], v[130:133], v[54:57]
	v_add_f32_e64 v78, v150, v124
	v_add_f32_e64 v79, v151, v125
	v_pk_add_f32 v[78:79], v[152:153], v[78:79]
	s_waitcnt lgkmcnt(6)
	v_mfma_f32_16x16x32_bf16 v[46:49], v[14:17], v[70:73], v[46:49]
	v_mul_f32_e64 v16, v44, v76
	v_mul_f32_e64 v17, v45, v76
	v_pk_mul_f32 v[14:15], v[42:43], v[76:77] op_sel_hi:[1,0]
	v_pk_add_f32 v[74:75], v[134:135], v[78:79]
	v_mfma_f32_16x16x32_bf16 v[50:53], v[66:69], v[130:133], v[50:53]
	v_add_f32_e64 v74, v154, v74
	v_add_f32_e64 v75, v155, v75
	v_pk_add_f32 v[66:67], v[156:157], v[74:75]
	s_waitcnt lgkmcnt(4)
	v_mfma_f32_16x16x32_bf16 v[42:45], v[10:13], v[70:73], v[14:17]
	v_mul_f32_e64 v12, v40, v76
	v_mul_f32_e64 v13, v41, v76
	v_pk_mul_f32 v[10:11], v[38:39], v[76:77] op_sel_hi:[1,0]
	v_pk_add_f32 v[14:15], v[158:159], v[66:67]
	s_waitcnt lgkmcnt(2)
	v_mfma_f32_16x16x32_bf16 v[38:41], v[6:9], v[70:73], v[10:13]
	v_mul_f32_e64 v8, v36, v76
	v_mul_f32_e64 v9, v37, v76
	v_pk_mul_f32 v[6:7], v[34:35], v[76:77] op_sel_hi:[1,0]
	v_pk_fma_f32 v[98:99], v[98:99], v[136:137], v[14:15]
	s_waitcnt lgkmcnt(0)
	v_mfma_f32_16x16x32_bf16 v[34:37], v[2:5], v[70:73], v[6:9]
	v_mov_b32_e32 v125, v129
	v_mov_b32_e32 v124, v160
	s_branch .LBB0_300
.Lna_dma_only:
	s_add_i32 s0, s65, 4
	s_cmp_ge_i32 s0, s26
	s_cbranch_scc0 .Lna_tile_b
	s_mul_hi_u32 s0, s64, 0xaaaaaaab
	s_lshr_b32 s0, s0, 1
	s_mul_i32 s0, s0, 0xc000
	s_add_i32 s14, s51, s65
	s_sub_i32 s0, s53, s0
	s_mul_hi_u32 s15, s14, 0x48000
	s_mul_i32 s14, s14, 0x48000
	s_add_u32 s60, s34, s14
	s_addc_u32 s61, s35, s15
	s_add_u32 s66, s30, s14
	s_addc_u32 s67, s31, s15
	s_mov_b32 m0, s0
	s_nop 0
	global_load_lds_dwordx4 v84, s[60:61]
	s_add_u32 m0, m0, 0x2000
	s_nop 0
	global_load_lds_dwordx4 v85, s[66:67]
	s_branch .Lna_dmadone_b

; template <int MODE> ...
;     ...
;     for (int jj = 0; jj < 2; ++jj) {
; #pragma unroll
;         for (int dt = 0; dt < 4; ++dt) o[jj][dt] = (f32x4){0.f, 0.f, 0.f, 0.f};
;         mrun[jj] = (MODE == 1) ? sink2 : -1e30f; lrun[jj] = (MODE == 1 && g == 0) ? 1.0f : 0.0f; }
.Lna_dmadone_b:
	s_branch .LBB0_300
.LBB0_307:
	v_mov_b32_e32 v9, 0
	v_mov_b32_e32 v8, v9
	v_mov_b32_e32 v7, v9
	v_mov_b32_e32 v6, v9
	v_mov_b32_e32 v17, v9
	v_mov_b32_e32 v16, v9
	v_mov_b32_e32 v15, v9
	v_mov_b32_e32 v14, v9
	v_mov_b32_e32 v13, v9
	v_mov_b32_e32 v12, v9
	v_mov_b32_e32 v11, v9
	v_mov_b32_e32 v10, v9
	v_mov_b32_e32 v5, v9
	v_mov_b32_e32 v4, v9
	v_mov_b32_e32 v3, v9
	v_mov_b32_e32 v2, v9

; __global__ void __launch_bounds__(NWAVES * 64, 2) fwd_kernel(Args args) {
	.amdhsa_kernel _Z10fwd_kernel4Args
		.amdhsa_group_segment_fixed_size 0
		.amdhsa_private_segment_fixed_size 0
		.amdhsa_kernarg_size 400
		.amdhsa_user_sgpr_count 2
		.amdhsa_user_sgpr_dispatch_ptr 0
		.amdhsa_user_sgpr_queue_ptr 0
		.amdhsa_user_sgpr_kernarg_segment_ptr 1
		.amdhsa_user_sgpr_dispatch_id 0
		.amdhsa_user_sgpr_kernarg_preload_length 0
		.amdhsa_user_sgpr_kernarg_preload_offset 0
		.amdhsa_user_sgpr_private_segment_size 0
		.amdhsa_uses_dynamic_stack 0
		.amdhsa_enable_private_segment 0
		.amdhsa_system_sgpr_workgroup_id_x 1
		.amdhsa_system_sgpr_workgroup_id_y 0
		.amdhsa_system_sgpr_workgroup_id_z 0
		.amdhsa_system_sgpr_workgroup_info 0
		.amdhsa_system_vgpr_workitem_id 0
		.amdhsa_next_free_vgpr 256
		.amdhsa_next_free_sgpr 102
		.amdhsa_accum_offset 256
		.amdhsa_reserve_vcc 1
		.amdhsa_float_round_mode_32 0
		.amdhsa_float_round_mode_16_64 0
		.amdhsa_float_denorm_mode_32 3
		.amdhsa_float_denorm_mode_16_64 3
		.amdhsa_dx10_clamp 1
		.amdhsa_ieee_mode 1
		.amdhsa_fp16_overflow 0
		.amdhsa_tg_split 0
		.amdhsa_exception_fp_ieee_invalid_op 0
		.amdhsa_exception_fp_denorm_src 0
		.amdhsa_exception_fp_ieee_div_zero 0
		.amdhsa_exception_fp_ieee_overflow 0
		.amdhsa_exception_fp_ieee_underflow 0
		.amdhsa_exception_fp_ieee_inexact 0
		.amdhsa_exception_int_div_zero 0
	.end_amdhsa_kernel

; __global__ void __launch_bounds__(NWAVES * 64, 2) fwd_kernel(Args args) {
amdhsa.kernels:
  - .agpr_count:     0
    .args:
      - .offset:         0
        .size:           144
        .value_kind:     by_value
      - .offset:         144
        .size:           4
        .value_kind:     hidden_block_count_x
      - .offset:         148
        .size:           4
        .value_kind:     hidden_block_count_y
      - .offset:         152
        .size:           4
        .value_kind:     hidden_block_count_z
      - .offset:         156
        .size:           2
        .value_kind:     hidden_group_size_x
      - .offset:         158
        .size:           2
        .value_kind:     hidden_group_size_y
      - .offset:         160
        .size:           2
        .value_kind:     hidden_group_size_z
      - .offset:         162
        .size:           2
        .value_kind:     hidden_remainder_x
      - .offset:         164
        .size:           2
        .value_kind:     hidden_remainder_y
      - .offset:         166
        .size:           2
        .value_kind:     hidden_remainder_z
      - .offset:         184
        .size:           8
        .value_kind:     hidden_global_offset_x
      - .offset:         192
        .size:           8
        .value_kind:     hidden_global_offset_y
      - .offset:         200
        .size:           8
        .value_kind:     hidden_global_offset_z
      - .offset:         208
        .size:           2
        .value_kind:     hidden_grid_dims
      - .offset:         264
        .size:           4
        .value_kind:     hidden_dynamic_lds_size
    .group_segment_fixed_size: 0
    .kernarg_segment_align: 8
    .kernarg_segment_size: 400
    .language:       OpenCL C
    .language_version:
      - 2
      - 0
    .max_flat_workgroup_size: 512
    .name:           _Z10fwd_kernel4Args
    .private_segment_fixed_size: 0
    .sgpr_count:     108
    .sgpr_spill_count: 214
    .symbol:         _Z10fwd_kernel4Args.kd
    .uniform_work_group_size: 1
    .uses_dynamic_stack: false
    .vgpr_count:     256
    .vgpr_spill_count: 0
    .wavefront_size: 64
